# diff attention: row-max reduction split into two independent chains (half the dependency depth)
# speedup vs baseline: 1.0088x; 1.0031x over previous
; __device__ __forceinline__ s16x4 vtr(const ALDS unsigned char* p) { return __builtin_bit_cast(s16x4, __builtin_amdgcn_ds_read_tr16_b64_v4i16((ALDS s16x4*)p)); }
; template <int DV, bool BAND> ...
;     ...
;         const bool first = (!BAND) && (t == t0);
;         const float dl = first ? mx : ((mx > THR) ? mx : 0.f);
;         if (__any(dl != 0.f)) {
;             m += dl;
; #pragma unroll
;             for (int r = 0; r < 16; ++r) { p0[r] -= dl; p1[r] -= dl; negm[r] = -m; }
;             const float f = first ? 1.f : __builtin_amdgcn_exp2f(-dl);
;             l *= f;
; #pragma unroll
;             for (int db = 0; db < NDB; ++db)
; #pragma unroll
;                 for (int r = 0; r < 16; ++r) o[db][r] *= f;
;         }
;         float ssum = 0.f;
;         bf16x8 pfs[4];
;     ...
;         ATT_EXP_SLICE(p0, 0, pfs[0]);
; #pragma unroll
;         for (int ks = 0; ks < 4; ++ks) {
;             if (ks + 1 < 4) {
; #pragma unroll
;                 for (int db = 0; db < NDB; ++db) { vlo[(ks + 1) & 1][db] = vtr(sb + va[db] + (ks + 1) * (16 * ROWB)); vhh[(ks + 1) & 1][db] = vtr(sb + va[db] + (ks + 1) * (16 * ROWB) + 4 * ROWB); }
;             }
; #pragma unroll
;             for (int db = 0; db < NDB; ++db) {
;                 const s16x4 lo = vlo[ks & 1][db], hh = vhh[ks & 1][db];
;                 const bf16x8 vf = (bf16x8){lo[0], lo[1], lo[2], lo[3], hh[0], hh[1], hh[2], hh[3]};
;                 o[db] = __builtin_amdgcn_mfma_f32_32x32x16_bf16(vf, pfs[ks], o[db], 0, 0, 0);
;             }
;             if (ks == 0) ATT_EXP_SLICE(p0, 8, pfs[1]);
;             if (ks == 1) ATT_EXP_SLICE(p1, 0, pfs[2]);
;             if (ks == 2) ATT_EXP_SLICE(p1, 8, pfs[3]);
;         }
;     ...
;         l += ssum;
;         s_cur = (s_cur == 2 * SLOT) ? 0 : s_cur + SLOT; s_n2 = (s_n2 == 2 * SLOT) ? 0 : s_n2 + SLOT;
;     }
.LBB0_773:
	s_waitcnt vmcnt(4)
	s_barrier
	s_setprio 0
	v_exp_f32_e32 v101, v84
	v_exp_f32_e32 v103, v85
	v_exp_f32_e32 v85, v86
	v_exp_f32_e32 v87, v87
	v_exp_f32_e32 v100, v88
	v_exp_f32_e32 v102, v89
	v_exp_f32_e32 v84, v90
	v_exp_f32_e32 v86, v91
	v_cvt_pk_bf16_f32 v88, v101, v103
	v_cvt_pk_bf16_f32 v89, v85, v87
	v_cvt_pk_bf16_f32 v90, v100, v102
	v_cvt_pk_bf16_f32 v91, v84, v86
	ds_read_b64_tr_b16 v[110:111], v108 offset:20480
	ds_read_b64_tr_b16 v[112:113], v108 offset:21504
	ds_read_b64_tr_b16 v[130:131], v107 offset:4096
	ds_read_b64_tr_b16 v[132:133], v107 offset:5120
	ds_read_b64_tr_b16 v[134:135], v106 offset:4096
	ds_read_b64_tr_b16 v[136:137], v106 offset:5120
	ds_read_b64_tr_b16 v[138:139], v67 offset:4096
	ds_read_b64_tr_b16 v[140:141], v67 offset:5120
	s_waitcnt lgkmcnt(14)
	v_mfma_f32_32x32x16_bf16 v[50:65], v[14:17], v[88:91], 0
	v_exp_f32_e32 v105, v92
	v_exp_f32_e32 v93, v93
	v_exp_f32_e32 v104, v94
	v_exp_f32_e32 v92, v95
	ds_read_b64_tr_b16 v[142:143], v108 offset:24576
	ds_read_b64_tr_b16 v[144:145], v108 offset:25600
	ds_read_b64_tr_b16 v[160:161], v107 offset:8192
	ds_read_b64_tr_b16 v[162:163], v107 offset:9216
	ds_read_b64_tr_b16 v[164:165], v106 offset:8192
	ds_read_b64_tr_b16 v[166:167], v106 offset:9216
	ds_read_b64_tr_b16 v[168:169], v67 offset:8192
	ds_read_b64_tr_b16 v[170:171], v67 offset:9216
	v_cvt_pk_bf16_f32 v94, v105, v93
	v_exp_f32_e32 v0, v76
	s_waitcnt lgkmcnt(14)
	v_mfma_f32_32x32x16_bf16 v[34:49], v[10:13], v[88:91], 0
	v_cvt_pk_bf16_f32 v95, v104, v92
	v_exp_f32_e32 v76, v77
	v_exp_f32_e32 v78, v78
	v_exp_f32_e32 v80, v80
	v_exp_f32_e32 v82, v82
	s_mov_b32 s4, 1
	s_mov_b32 s5, 0x18000
	v_mfma_f32_32x32x16_bf16 v[18:33], v[2:5], v[88:91], 0
	s_mov_b32 s6, 0x8000
	s_movk_i32 s49, 0x900
	v_mfma_f32_32x32x16_bf16 v[2:17], v[6:9], v[88:91], 0
	v_exp_f32_e32 v89, v96
	v_exp_f32_e32 v91, v97
	v_exp_f32_e32 v88, v98
	v_exp_f32_e32 v90, v99
	v_exp_f32_e32 v99, v68
	v_cvt_pk_bf16_f32 v96, v89, v91
	v_exp_f32_e32 v98, v79
	v_cvt_pk_bf16_f32 v97, v88, v90
	s_nop 1
	v_mfma_f32_32x32x16_bf16 v[50:65], v[110:113], v[94:97], v[50:65]
	v_exp_f32_e32 v113, v69
	v_exp_f32_e32 v112, v83
	v_cvt_pk_bf16_f32 v68, v99, v113
	s_waitcnt lgkmcnt(12)
	v_mfma_f32_32x32x16_bf16 v[34:49], v[130:133], v[94:97], v[34:49]
	s_waitcnt lgkmcnt(10)
	v_mfma_f32_32x32x16_bf16 v[18:33], v[134:137], v[94:97], v[18:33]
	v_exp_f32_e32 v134, v70
	v_exp_f32_e32 v135, v71
	v_exp_f32_e32 v136, v72
	v_exp_f32_e32 v137, v73
	v_cvt_pk_bf16_f32 v69, v134, v135
	v_cvt_pk_bf16_f32 v70, v136, v137
	s_waitcnt lgkmcnt(8)
	v_mfma_f32_32x32x16_bf16 v[2:17], v[138:141], v[94:97], v[2:17]
	v_exp_f32_e32 v138, v74
	v_exp_f32_e32 v139, v75
	ds_read_b64_tr_b16 v[72:73], v108 offset:28672
	ds_read_b64_tr_b16 v[74:75], v108 offset:29696
	ds_read_b64_tr_b16 v[94:95], v107 offset:12288
	ds_read_b64_tr_b16 v[96:97], v107 offset:13312
	ds_read_b64_tr_b16 v[108:109], v106 offset:12288
	ds_read_b64_tr_b16 v[110:111], v106 offset:13312
	ds_read_b64_tr_b16 v[130:131], v67 offset:12288
	ds_read_b64_tr_b16 v[132:133], v67 offset:13312
	v_exp_f32_e32 v106, v81
	v_add_f32_e32 v81, v113, v99
	v_cvt_pk_bf16_f32 v71, v138, v139
	v_add_f32_e32 v107, v135, v134
	v_add_f32_e32 v83, v137, v136
	s_waitcnt lgkmcnt(14)
	v_mfma_f32_32x32x16_bf16 v[50:65], v[142:145], v[68:71], v[50:65]
	v_add_f32_e32 v113, v139, v138
	v_mov_b32_e32 v67, v66
	s_waitcnt lgkmcnt(12)
	v_mfma_f32_32x32x16_bf16 v[34:49], v[160:163], v[68:71], v[34:49]
	s_waitcnt lgkmcnt(10)
	v_mfma_f32_32x32x16_bf16 v[18:33], v[164:167], v[68:71], v[18:33]
	s_waitcnt lgkmcnt(8)
	v_mfma_f32_32x32x16_bf16 v[2:17], v[168:171], v[68:71], v[2:17]
	v_cvt_pk_bf16_f32 v68, v0, v76
	v_cvt_pk_bf16_f32 v69, v78, v98
	v_cvt_pk_bf16_f32 v70, v80, v106
	v_cvt_pk_bf16_f32 v71, v82, v112
	s_waitcnt lgkmcnt(6)
	s_nop 0
	v_mfma_f32_32x32x16_bf16 v[50:65], v[72:75], v[68:71], v[50:65]
	v_add_f32_e64 v72, v102, v100
	v_add_f32_e64 v73, v103, v101
	v_add_f32_e64 v74, v86, v84
	v_add_f32_e64 v75, v87, v85
	v_add_f32_e64 v72, v74, v72
	v_add_f32_e64 v73, v75, v73
	v_pk_add_f32 v[74:75], v[106:107], v[80:81]
	v_pk_add_f32 v[72:73], v[72:73], v[72:73] op_sel_hi:[0,1]
	v_mov_b32_e32 v77, v73
	s_waitcnt lgkmcnt(4)
	v_mfma_f32_32x32x16_bf16 v[34:49], v[94:97], v[68:71], v[34:49]
	v_add_f32_e64 v80, v112, v82
	v_add_f32_e64 v81, v113, v83
	v_mov_b32_e32 v72, v66
	v_add_f32_e64 v74, v80, v74
	v_add_f32_e64 v75, v81, v75
	v_mov_b32_e32 v73, v66
	v_mov_b32_e32 v80, v66
	v_mov_b32_e32 v81, v66
	s_waitcnt lgkmcnt(2)
	v_mfma_f32_32x32x16_bf16 v[18:33], v[108:111], v[68:71], v[18:33]
	s_waitcnt lgkmcnt(0)
	v_mfma_f32_32x32x16_bf16 v[2:17], v[130:133], v[68:71], v[2:17]
	v_add_f32_e64 v68, v92, v104
	v_add_f32_e64 v69, v93, v105
	v_add_f32_e64 v70, v90, v88
	v_add_f32_e64 v71, v91, v89
	v_pk_add_f32 v[68:69], v[68:69], v[68:69] op_sel_hi:[0,1]
	v_pk_add_f32 v[70:71], v[70:71], v[70:71] op_sel_hi:[0,1]
	v_mov_b32_e32 v99, v71
	v_mov_b32_e32 v79, v69
	v_pk_add_f32 v[68:69], v[98:99], v[78:79]
	v_pk_add_f32 v[70:71], v[76:77], v[0:1]
	v_mov_b32_e32 v76, v66
	v_pk_add_f32 v[68:69], v[68:69], v[70:71]
	v_mov_b32_e32 v70, v66
	v_pk_add_f32 v[68:69], v[74:75], v[68:69]
	v_mov_b32_e32 v71, v66
	v_add_f32_e32 v160, v68, v69
	v_mov_b32_e32 v68, v66
	v_mov_b32_e32 v69, v66
	v_mov_b32_e32 v74, v66
	v_mov_b32_e32 v75, v66
	v_mov_b32_e32 v77, v66
	v_mov_b32_e32 v78, v66
	v_mov_b32_e32 v79, v66
	s_branch .LBB0_775
; __device__ __forceinline__ s16x4 vtr(const ALDS unsigned char* p) { return __builtin_bit_cast(s16x4, __builtin_amdgcn_ds_read_tr16_b64_v4i16((ALDS s16x4*)p)); }
; template <int DV, bool BAND> ...
;     ...
;         float ssum = 0.f;
;         bf16x8 pfs[4];
;     ...
;         ATT_EXP_SLICE(p0, 0, pfs[0]);
; #pragma unroll
;         for (int ks = 0; ks < 4; ++ks) {
;             if (ks + 1 < 4) {
; #pragma unroll
;                 for (int db = 0; db < NDB; ++db) { vlo[(ks + 1) & 1][db] = vtr(sb + va[db] + (ks + 1) * (16 * ROWB)); vhh[(ks + 1) & 1][db] = vtr(sb + va[db] + (ks + 1) * (16 * ROWB) + 4 * ROWB); }
;             }
; #pragma unroll
;             for (int db = 0; db < NDB; ++db) {
;                 const s16x4 lo = vlo[ks & 1][db], hh = vhh[ks & 1][db];
;                 const bf16x8 vf = (bf16x8){lo[0], lo[1], lo[2], lo[3], hh[0], hh[1], hh[2], hh[3]};
;                 o[db] = __builtin_amdgcn_mfma_f32_32x32x16_bf16(vf, pfs[ks], o[db], 0, 0, 0);
;             }
;             if (ks == 0) ATT_EXP_SLICE(p0, 8, pfs[1]);
;             if (ks == 1) ATT_EXP_SLICE(p1, 0, pfs[2]);
;             if (ks == 2) ATT_EXP_SLICE(p1, 8, pfs[3]);
;         }
;     ...
;         l += ssum;
;         s_cur = (s_cur == 2 * SLOT) ? 0 : s_cur + SLOT; s_n2 = (s_n2 == 2 * SLOT) ? 0 : s_n2 + SLOT;
;     }
.LBB0_774:
	s_cmp_eq_u32 s4, 63
	s_cbranch_scc1 .Ldiff_b2_nowait
	s_waitcnt vmcnt(4)
.Ldiff_b2_nowait:
	s_barrier
	s_setprio 0
	v_exp_f32_e32 v167, v98
	v_exp_f32_e32 v169, v99
	v_exp_f32_e32 v171, v100
	v_exp_f32_e32 v173, v101
	v_exp_f32_e32 v166, v102
	v_exp_f32_e32 v168, v103
	v_exp_f32_e32 v170, v104
	v_exp_f32_e32 v172, v105
	v_cvt_pk_bf16_f32 v98, v167, v169
	v_cvt_pk_bf16_f32 v99, v171, v173
	v_cvt_pk_bf16_f32 v100, v166, v168
	v_cvt_pk_bf16_f32 v101, v170, v172
	ds_read_b64_tr_b16 v[102:103], v164 offset:20480
	ds_read_b64_tr_b16 v[104:105], v164 offset:21504
	s_waitcnt lgkmcnt(8)
	v_mfma_f32_32x32x16_bf16 v[50:65], v[142:145], v[98:101], v[50:65]
	v_exp_f32_e32 v142, v82
	v_exp_f32_e32 v143, v83
	v_exp_f32_e32 v144, v84
	v_exp_f32_e32 v145, v85
	v_exp_f32_e32 v165, v86
	v_exp_f32_e32 v174, v87
	v_exp_f32_e32 v175, v88
	s_waitcnt lgkmcnt(6)
	v_mfma_f32_32x32x16_bf16 v[34:49], v[138:141], v[98:101], v[34:49]
	v_exp_f32_e32 v139, v110
	v_exp_f32_e32 v141, v111
	v_exp_f32_e32 v138, v112
	v_exp_f32_e32 v140, v113
	v_exp_f32_e32 v176, v89
	v_cvt_pk_bf16_f32 v86, v142, v143
	v_cvt_pk_bf16_f32 v87, v144, v145
	s_waitcnt lgkmcnt(4)
	v_mfma_f32_32x32x16_bf16 v[18:33], v[134:137], v[98:101], v[18:33]
	v_exp_f32_e32 v135, v106
	v_exp_f32_e32 v137, v107
	v_exp_f32_e32 v134, v108
	v_exp_f32_e32 v136, v109
	ds_read_b64_tr_b16 v[106:107], v164 offset:24576
	ds_read_b64_tr_b16 v[108:109], v164 offset:25600
	v_cvt_pk_bf16_f32 v88, v165, v174
	v_cvt_pk_bf16_f32 v89, v175, v176
	s_waitcnt lgkmcnt(4)
	v_mfma_f32_32x32x16_bf16 v[2:17], v[130:133], v[98:101], v[2:17]
	v_cvt_pk_bf16_f32 v98, v135, v137
	v_cvt_pk_bf16_f32 v99, v134, v136
	v_cvt_pk_bf16_f32 v100, v139, v141
	v_cvt_pk_bf16_f32 v101, v138, v140
	v_add_f32_e64 v82, v168, v166
	v_add_f32_e64 v83, v169, v167
	v_exp_f32_e32 v0, v90
	v_exp_f32_e32 v90, v94
	s_waitcnt lgkmcnt(2)
	v_mfma_f32_32x32x16_bf16 v[50:65], v[102:105], v[98:101], v[50:65]
	ds_read_b64_tr_b16 v[102:103], v163 offset:4096
	ds_read_b64_tr_b16 v[104:105], v163 offset:5120
	ds_read_b64_tr_b16 v[110:111], v164 offset:29696
	v_exp_f32_e32 v94, v96
	v_exp_f32_e32 v96, v97
	v_add_f32_e32 v97, v176, v175
	s_add_i32 s7, s6, 0x8000
	s_cmp_lg_u32 s6, 0x18000
	s_cselect_b32 s6, s7, 0
	s_waitcnt lgkmcnt(1)
	v_mfma_f32_32x32x16_bf16 v[34:49], v[102:105], v[98:101], v[34:49]
	ds_read_b64_tr_b16 v[102:103], v161 offset:4096
	ds_read_b64_tr_b16 v[104:105], v161 offset:5120
	ds_read_b64_tr_b16 v[130:131], v161 offset:8192
	ds_read_b64_tr_b16 v[132:133], v161 offset:9216
	s_add_i32 s7, s5, 0x8000
	s_cmp_lg_u32 s5, 0x18000
	s_cselect_b32 s5, s7, 0
	s_add_i32 s4, s4, 1
	s_cmp_lg_u32 s4, 64
	s_waitcnt lgkmcnt(2)
	v_mfma_f32_32x32x16_bf16 v[18:33], v[102:105], v[98:101], v[18:33]
	ds_read_b64_tr_b16 v[102:103], v162 offset:4096
	ds_read_b64_tr_b16 v[104:105], v162 offset:5120
	ds_read_b64_tr_b16 v[84:85], v161 offset:13312
	s_waitcnt lgkmcnt(1)
	v_mfma_f32_32x32x16_bf16 v[2:17], v[102:105], v[98:101], v[2:17]
	v_add_f32_e64 v102, v172, v170
	v_add_f32_e64 v103, v173, v171
	v_add_f32_e64 v82, v102, v82
	v_add_f32_e64 v83, v103, v83
	v_mfma_f32_32x32x16_bf16 v[50:65], v[106:109], v[86:89], v[50:65]
	ds_read_b64_tr_b16 v[98:99], v163 offset:8192
	ds_read_b64_tr_b16 v[100:101], v163 offset:9216
	ds_read_b64_tr_b16 v[108:109], v164 offset:28672
	ds_read_b64_tr_b16 v[102:103], v163 offset:12288
	ds_read_b64_tr_b16 v[104:105], v163 offset:13312
	v_pk_add_f32 v[106:107], v[82:83], v[82:83] op_sel_hi:[0,1]
	v_pk_add_f32 v[82:83], v[136:137], v[134:135]
	v_exp_f32_e32 v106, v91
	v_pk_add_f32 v[112:113], v[82:83], v[82:83] op_sel_hi:[0,1]
	v_pk_add_f32 v[82:83], v[140:141], v[138:139]
	s_waitcnt lgkmcnt(3)
	v_mfma_f32_32x32x16_bf16 v[34:49], v[98:101], v[86:89], v[34:49]
	ds_read_b64_tr_b16 v[98:99], v162 offset:8192
	ds_read_b64_tr_b16 v[100:101], v162 offset:9216
	v_add_f32_e64 v134, v82, v82
	v_add_f32_e64 v135, v82, v83
	v_exp_f32_e32 v112, v92
	v_exp_f32_e32 v134, v93
	v_exp_f32_e32 v92, v95
	v_add_f32_e32 v91, v143, v142
	v_add_f32_e32 v93, v145, v144
	v_mfma_f32_32x32x16_bf16 v[18:33], v[130:133], v[86:89], v[18:33]
	ds_read_b64_tr_b16 v[130:131], v162 offset:12288
	ds_read_b64_tr_b16 v[132:133], v162 offset:13312
	ds_read_b64_tr_b16 v[82:83], v161 offset:12288
	v_add_f32_e32 v95, v174, v165
	s_waitcnt lgkmcnt(3)
	v_mfma_f32_32x32x16_bf16 v[2:17], v[98:101], v[86:89], v[2:17]
	v_cvt_pk_bf16_f32 v86, v0, v106
	v_cvt_pk_bf16_f32 v87, v112, v134
	v_cvt_pk_bf16_f32 v88, v90, v92
	v_cvt_pk_bf16_f32 v89, v94, v96
	v_add_f32_e64 v98, v106, v0
	v_add_f32_e64 v99, v107, v1
	v_pk_add_f32 v[100:101], v[134:135], v[112:113]
	v_pk_add_f32 v[90:91], v[92:93], v[90:91]
	v_mfma_f32_32x32x16_bf16 v[50:65], v[108:111], v[86:89], v[50:65]
	v_add_f32_e64 v92, v96, v94
	v_add_f32_e64 v93, v97, v95
	v_add_f32_e64 v98, v100, v98
	v_add_f32_e64 v99, v101, v99
	v_add_f32_e64 v90, v92, v90
	v_add_f32_e64 v91, v93, v91
	v_pk_add_f32 v[90:91], v[90:91], v[98:99]
	s_nop 0
	v_add_f32_e32 v0, v90, v91
	v_mfma_f32_32x32x16_bf16 v[34:49], v[102:105], v[86:89], v[34:49]
	v_add_f32_e32 v160, v160, v0
	s_waitcnt lgkmcnt(0)
	v_mfma_f32_32x32x16_bf16 v[18:33], v[82:85], v[86:89], v[18:33]
	v_mfma_f32_32x32x16_bf16 v[2:17], v[130:133], v[86:89], v[2:17]
	s_cbranch_scc0 .LBB0_777

; __device__ __forceinline__ float halfswap_max(float v) { auto rr = __builtin_amdgcn_permlane32_swap(__float_as_uint(v), __float_as_uint(v), false, false); return fmaxf(__uint_as_float(rr[0]), __uint_as_float(rr[1])); }
; template <int DV, bool BAND> ...
;     ...
;         ATT_PIECE(0, tn, s_n2); ATT_PIECE(1, tn, s_n2); ATT_PIECE(2, tn, s_n2); ATT_PIECE(3, tn, s_n2);
;         __builtin_amdgcn_sched_barrier(0);
;         if (BAND) {
;             if (t == tq - 2 || t == tq + 2) {
;                 const int rel0 = t * 64 + 8 * hi - qpos;
; #pragma unroll
;                 for (int r = 0; r < 16; ++r) { const int rel = rel0 + 16 * (r >> 3) + (r & 7);
;                     if (rel < -128 || rel > 128) p0[r] = -INFINITY;
;                     if (rel + 32 < -128 || rel + 32 > 128) p1[r] = -INFINITY; }
;             }
;         }
;         float mx = fmaxf(p0[0], p1[0]);
; #pragma unroll
;         for (int r = 1; r < 16; ++r) mx = fmaxf(fmaxf(mx, p0[r]), p1[r]);
;         mx = halfswap_max(mx);
;         const bool first = (!BAND) && (t == t0);
;         const float dl = first ? mx : ((mx > THR) ? mx : 0.f);
;         if (__any(dl != 0.f)) {
;             m += dl;
; #pragma unroll
;             for (int r = 0; r < 16; ++r) { p0[r] -= dl; p1[r] -= dl; negm[r] = -m; }
;             const float f = first ? 1.f : __builtin_amdgcn_exp2f(-dl);
;             l *= f;
; #pragma unroll
;             for (int db = 0; db < NDB; ++db)
; #pragma unroll
;                 for (int r = 0; r < 16; ++r) o[db][r] *= f;
;         }
.Ldiff_pf_join:
	s_add_u32 s8, s7, 0x90000
	s_addc_u32 s9, s12, 0
	s_add_i32 s13, s5, s30
	s_mov_b32 s10, m0
	s_mov_b32 m0, s13
	s_nop 0
	global_load_lds_dwordx4 v151, s[8:9]
	s_mov_b32 m0, s10
	s_add_u32 s10, s7, 0x90080
	s_addc_u32 s11, s12, 0
	s_addk_i32 s13, 0x2000
	s_mov_b32 s14, m0
	s_mov_b32 m0, s13
	s_nop 0
	global_load_lds_dwordx4 v151, s[10:11]
	s_mov_b32 m0, s14
	s_add_i32 s10, s5, s84
	s_mov_b32 s11, m0
	s_mov_b32 m0, s10
	s_nop 0
	global_load_lds_dwordx4 v152, s[8:9]
	s_mov_b32 m0, s11
	s_add_u32 s8, s7, 0x94800
	s_addc_u32 s9, s12, 0
	s_addk_i32 s10, 0x400
	s_mov_b32 s7, m0
	s_mov_b32 m0, s10
	s_nop 0
	global_load_lds_dwordx4 v152, s[8:9]
	s_mov_b32 m0, s7
	v_max3_f32 v165, v98, v99, v100
	v_max3_f32 v0, v82, v83, v84
	v_max3_f32 v165, v165, v101, v102
	v_max3_f32 v0, v0, v85, v86
	v_max3_f32 v165, v165, v103, v104
	v_max3_f32 v0, v0, v87, v88
	v_max3_f32 v165, v165, v105, v106
	v_max3_f32 v0, v0, v89, v90
	v_max3_f32 v165, v165, v107, v108
	v_max3_f32 v0, v0, v91, v92
	v_max3_f32 v165, v165, v109, v110
	v_max3_f32 v0, v0, v93, v94
	v_max3_f32 v165, v165, v111, v112
	v_max3_f32 v0, v0, v95, v96
	v_max_f32_e32 v165, v165, v113
	v_max_f32_e32 v0, v0, v97
	v_max_f32_e32 v0, v0, v165
	v_mov_b32_e32 v165, v0
	s_nop 1
	v_permlane32_swap_b32_e32 v0, v165
	v_max_f32_e32 v165, v165, v165
	v_max_f32_e32 v0, v0, v0
	v_max_f32_e32 v0, v0, v165
	v_cmp_lt_f32_e32 vcc, s31, v0
	s_cbranch_vccz .LBB0_774
	s_nop 1
	v_cndmask_b32_e32 v0, 0, v0, vcc
	s_nop 0
	v_exp_f32_e64 v68, -v0
	v_add_f32_e32 v159, v159, v0
	v_xor_b32_e32 v66, 0x80000000, v159
	v_pk_add_f32 v[98:99], v[98:99], v[0:1] op_sel_hi:[1,0] neg_lo:[0,1] neg_hi:[0,1]
	v_pk_add_f32 v[82:83], v[82:83], v[0:1] op_sel_hi:[1,0] neg_lo:[0,1] neg_hi:[0,1]
	v_pk_add_f32 v[100:101], v[100:101], v[0:1] op_sel_hi:[1,0] neg_lo:[0,1] neg_hi:[0,1]
	v_pk_add_f32 v[84:85], v[84:85], v[0:1] op_sel_hi:[1,0] neg_lo:[0,1] neg_hi:[0,1]
	v_pk_add_f32 v[102:103], v[102:103], v[0:1] op_sel_hi:[1,0] neg_lo:[0,1] neg_hi:[0,1]
	v_pk_add_f32 v[86:87], v[86:87], v[0:1] op_sel_hi:[1,0] neg_lo:[0,1] neg_hi:[0,1]
	v_pk_add_f32 v[104:105], v[104:105], v[0:1] op_sel_hi:[1,0] neg_lo:[0,1] neg_hi:[0,1]
	v_pk_add_f32 v[88:89], v[88:89], v[0:1] op_sel_hi:[1,0] neg_lo:[0,1] neg_hi:[0,1]
	v_pk_add_f32 v[106:107], v[106:107], v[0:1] op_sel_hi:[1,0] neg_lo:[0,1] neg_hi:[0,1]
	v_pk_add_f32 v[90:91], v[90:91], v[0:1] op_sel_hi:[1,0] neg_lo:[0,1] neg_hi:[0,1]
	v_pk_add_f32 v[108:109], v[108:109], v[0:1] op_sel_hi:[1,0] neg_lo:[0,1] neg_hi:[0,1]
	v_pk_add_f32 v[92:93], v[92:93], v[0:1] op_sel_hi:[1,0] neg_lo:[0,1] neg_hi:[0,1]
	v_pk_add_f32 v[110:111], v[110:111], v[0:1] op_sel_hi:[1,0] neg_lo:[0,1] neg_hi:[0,1]
	v_pk_add_f32 v[94:95], v[94:95], v[0:1] op_sel_hi:[1,0] neg_lo:[0,1] neg_hi:[0,1]
	v_pk_add_f32 v[112:113], v[112:113], v[0:1] op_sel_hi:[1,0] neg_lo:[0,1] neg_hi:[0,1]
	v_pk_add_f32 v[96:97], v[96:97], v[0:1] op_sel_hi:[1,0] neg_lo:[0,1] neg_hi:[0,1]
	v_pk_mul_f32 v[64:65], v[64:65], v[68:69] op_sel_hi:[1,0]
	v_pk_mul_f32 v[62:63], v[62:63], v[68:69] op_sel_hi:[1,0]
	v_pk_mul_f32 v[60:61], v[60:61], v[68:69] op_sel_hi:[1,0]
	v_pk_mul_f32 v[58:59], v[58:59], v[68:69] op_sel_hi:[1,0]
	v_pk_mul_f32 v[56:57], v[56:57], v[68:69] op_sel_hi:[1,0]
	v_pk_mul_f32 v[54:55], v[54:55], v[68:69] op_sel_hi:[1,0]
	v_pk_mul_f32 v[52:53], v[52:53], v[68:69] op_sel_hi:[1,0]
	v_pk_mul_f32 v[50:51], v[50:51], v[68:69] op_sel_hi:[1,0]
	v_pk_mul_f32 v[48:49], v[48:49], v[68:69] op_sel_hi:[1,0]
	v_pk_mul_f32 v[46:47], v[46:47], v[68:69] op_sel_hi:[1,0]
	v_pk_mul_f32 v[44:45], v[44:45], v[68:69] op_sel_hi:[1,0]
	v_pk_mul_f32 v[42:43], v[42:43], v[68:69] op_sel_hi:[1,0]
	v_pk_mul_f32 v[40:41], v[40:41], v[68:69] op_sel_hi:[1,0]
	v_pk_mul_f32 v[38:39], v[38:39], v[68:69] op_sel_hi:[1,0]
	v_pk_mul_f32 v[36:37], v[36:37], v[68:69] op_sel_hi:[1,0]
	v_pk_mul_f32 v[34:35], v[34:35], v[68:69] op_sel_hi:[1,0]
	v_pk_mul_f32 v[32:33], v[32:33], v[68:69] op_sel_hi:[1,0]
	v_pk_mul_f32 v[30:31], v[30:31], v[68:69] op_sel_hi:[1,0]
	v_pk_mul_f32 v[28:29], v[28:29], v[68:69] op_sel_hi:[1,0]
	v_pk_mul_f32 v[26:27], v[26:27], v[68:69] op_sel_hi:[1,0]
	v_pk_mul_f32 v[24:25], v[24:25], v[68:69] op_sel_hi:[1,0]
	v_pk_mul_f32 v[22:23], v[22:23], v[68:69] op_sel_hi:[1,0]
	v_pk_mul_f32 v[20:21], v[20:21], v[68:69] op_sel_hi:[1,0]
	v_pk_mul_f32 v[18:19], v[18:19], v[68:69] op_sel_hi:[1,0]
	v_pk_mul_f32 v[16:17], v[16:17], v[68:69] op_sel_hi:[1,0]
	v_pk_mul_f32 v[14:15], v[14:15], v[68:69] op_sel_hi:[1,0]
	v_pk_mul_f32 v[12:13], v[12:13], v[68:69] op_sel_hi:[1,0]
	v_pk_mul_f32 v[10:11], v[10:11], v[68:69] op_sel_hi:[1,0]
	v_pk_mul_f32 v[8:9], v[8:9], v[68:69] op_sel_hi:[1,0]
	v_pk_mul_f32 v[6:7], v[6:7], v[68:69] op_sel_hi:[1,0]
	v_pk_mul_f32 v[4:5], v[4:5], v[68:69] op_sel_hi:[1,0]
	v_pk_mul_f32 v[2:3], v[2:3], v[68:69] op_sel_hi:[1,0]
	v_mul_f32_e32 v160, v160, v68
	v_mov_b32_e32 v67, v66
	v_mov_b32_e32 v68, v66
	v_mov_b32_e32 v69, v66
	v_mov_b32_e32 v70, v66
	v_mov_b32_e32 v71, v66
	v_mov_b32_e32 v72, v66
	v_mov_b32_e32 v73, v66
	v_mov_b32_e32 v74, v66
	v_mov_b32_e32 v75, v66
	v_mov_b32_e32 v76, v66
	v_mov_b32_e32 v77, v66
	v_mov_b32_e32 v78, v66
	v_mov_b32_e32 v79, v66
	v_mov_b32_e32 v80, v66
	v_mov_b32_e32 v81, v66
	s_branch .LBB0_774
